# conv_v70 + piece-blocked obuf for prompt rows (in place in P's dead q/k columns): phase-5 A-operand LDS-DMA reads full 128B lines; GDN/HGRN2 head-output stores retargeted
# speedup vs baseline: 1.0338x; 1.0130x over previous
.LBB0_1029:
	s_cmpk_gt_i32 s2, 0xfff
	s_cbranch_scc1 .LBB0_1032
	s_add_u32 s15, s20, 0x17348000
	s_addc_u32 s16, s21, 0
	s_add_u32 s100, s20, 0x10000
	s_addc_u32 s101, s21, 0
	s_waitcnt vmcnt(30)
	v_mbcnt_hi_u32_b32 v20, -1, v183
	s_add_u32 s17, s20, 0x15248000
	v_and_b32_e32 v0, 64, v20
	s_mov_b32 s0, 0x358637bd
	s_addc_u32 s29, s21, 0
	s_mov_b32 s9, 0
	v_mov_b32_e32 v9, 0
	s_mov_b64 s[10:11], 0x1000
	s_mov_b64 s[12:13], 0x1800
	s_movk_i32 s34, 0x1000
	v_xor_b32_e32 v21, 1, v20
	v_add_u32_e32 v22, 64, v0
	v_xor_b32_e32 v23, 2, v20
	s_waitcnt vmcnt(29)
	v_xor_b32_e32 v24, 4, v20
	v_xor_b32_e32 v25, 8, v20
	s_mov_b32 s14, 0x3c800000
	v_mov_b64_e32 v[10:11], s[0:1]
	s_mov_b32 s35, 0x800000
	s_movk_i32 s36, 0x2000
	s_movk_i32 s37, 0x4000
	s_movk_i32 s38, 0x6000
	s_mov_b32 s39, s2
.LBB0_1031:
	v_cmp_lt_i32_e32 vcc, v21, v22
	v_mov_b32_e32 v0, v181
	s_ashr_i32 s0, s39, 3
	v_cndmask_b32_e32 v2, v20, v21, vcc
	v_cmp_lt_i32_e32 vcc, v23, v22
	s_waitcnt vmcnt(28)
	v_lshlrev_b32_e32 v33, 2, v2
	v_ashrrev_i32_e32 v2, 6, v0
	v_cndmask_b32_e32 v3, v20, v23, vcc
	v_cmp_lt_i32_e32 vcc, v24, v22
	v_lshlrev_b32_e32 v32, 2, v3
	v_and_b32_e32 v3, 63, v0
	v_cndmask_b32_e32 v4, v20, v24, vcc
	v_cmp_lt_i32_e32 vcc, v25, v22
	v_lshlrev_b32_e32 v31, 2, v4
	v_and_b32_e32 v4, 15, v0
	v_cndmask_b32_e32 v5, v20, v25, vcc
	v_lshlrev_b32_e32 v30, 2, v5
	v_lshrrev_b32_e32 v0, 2, v0
	v_lshlrev_b32_e32 v5, 4, v2
	s_lshl_b32 s1, s39, 7
	v_and_b32_e32 v6, 12, v0
	v_lshlrev_b32_e32 v7, 2, v3
	v_lshlrev_b32_e32 v12, 5, v3
	v_lshl_add_u32 v3, s0, 6, v5
	s_and_b32 s4, s39, 0xfffffc00
	s_and_b32 s8, s1, 0x380
	v_lshlrev_b32_e32 v8, 1, v4
	v_lshlrev_b32_e32 v0, 2, v4
	v_or_b32_e32 v5, v5, v4
	v_or_b32_e32 v4, v3, v6
	s_and_b32 s1, s0, 0x7f
	s_or_b32 s4, s8, s4
	global_load_dword v29, v0, s[40:41]
	global_load_dword v28, v0, s[40:41] offset:64
	global_load_dword v27, v0, s[40:41] offset:128
	global_load_dword v26, v0, s[40:41] offset:192
	v_lshlrev_b32_e32 v0, 1, v6
	v_lshlrev_b32_e32 v6, 6, v5
	v_ashrrev_i32_e32 v5, 31, v4
	s_or_b32 s4, s4, s1
	s_waitcnt vmcnt(28)
	v_lshlrev_b64 v[66:67], 13, v[4:5]
	s_ashr_i32 s5, s4, 31
	v_or_b32_e32 v14, 1, v4
	v_or_b32_e32 v16, 2, v4
	v_or_b32_e32 v18, 3, v4
	v_lshl_add_u64 v[4:5], s[20:21], 0, v[66:67]
	s_lshl_b64 s[0:1], s[4:5], 13
	v_lshl_add_u64 v[4:5], v[4:5], 0, s[8:9]
	s_add_u32 s4, s50, s0
	v_lshl_add_u64 v[50:51], v[4:5], 0, v[8:9]
	s_addc_u32 s5, s51, s1
	v_add_co_u32_e32 v52, vcc, s36, v50
	s_add_u32 s6, s17, s0
	s_nop 0
	v_addc_co_u32_e32 v53, vcc, 0, v51, vcc
	v_lshl_or_b32 v2, v2, 10, v7
	v_ashrrev_i32_e32 v7, 31, v6
	s_addc_u32 s7, s29, s1
	v_add_co_u32_e32 v54, vcc, s37, v50
	v_mov_b32_e32 v1, v9
	v_ashrrev_i32_e32 v3, 31, v2
	v_lshl_add_u64 v[6:7], v[6:7], 1, s[4:5]
	s_add_u32 s0, s15, s0
	v_addc_co_u32_e32 v55, vcc, 0, v51, vcc
	v_mov_b32_e32 v13, v9
	v_lshl_add_u64 v[34:35], v[6:7], 0, v[0:1]
	v_lshl_add_u64 v[36:37], v[2:3], 1, s[6:7]
	s_addc_u32 s1, s16, s1
	v_add_co_u32_e32 v56, vcc, s38, v50
	global_load_dwordx2 v[4:5], v[34:35], off
	global_load_dwordx2 v[6:7], v[34:35], off offset:32
	global_load_dwordx2 v[0:1], v[34:35], off offset:64
	global_load_dwordx2 v[2:3], v[34:35], off offset:96
	global_load_dwordx2 v[68:69], v[36:37], off
	global_load_dwordx2 v[72:73], v[36:37], off offset:512
	global_load_dwordx2 v[76:77], v[36:37], off offset:1024
	global_load_dwordx2 v[80:81], v[36:37], off offset:1536
	v_addc_co_u32_e32 v57, vcc, 0, v51, vcc
	global_load_ushort v82, v[50:51], off offset:3072
	global_load_ushort v83, v[50:51], off offset:3104
	global_load_ushort v84, v[50:51], off offset:3136
	global_load_ushort v85, v[50:51], off offset:3168
	global_load_dwordx4 v[34:37], v12, s[0:1]
	global_load_dwordx4 v[38:41], v12, s[0:1] offset:2048
	global_load_dwordx4 v[42:45], v12, s[0:1] offset:16
	global_load_dwordx4 v[46:49], v12, s[0:1] offset:2064
	global_load_ushort v86, v[52:53], off offset:3072
	global_load_ushort v87, v[54:55], off offset:3072
	global_load_ushort v88, v[56:57], off offset:3072
	global_load_ushort v89, v[52:53], off offset:3104
	global_load_ushort v90, v[54:55], off offset:3104
	global_load_ushort v91, v[56:57], off offset:3104
	global_load_ushort v92, v[52:53], off offset:3136
	global_load_ushort v93, v[54:55], off offset:3136
	global_load_ushort v94, v[56:57], off offset:3136
	global_load_ushort v95, v[54:55], off offset:3168
	global_load_ushort v96, v[52:53], off offset:3168
	global_load_ushort v97, v[56:57], off offset:3168
	v_lshl_add_u64 v[12:13], s[0:1], 0, v[12:13]
	v_lshl_add_u64 v[70:71], v[12:13], 0, s[10:11]
	s_waitcnt vmcnt(55)
	v_lshl_add_u64 v[74:75], v[12:13], 0, s[12:13]
	v_add_co_u32_e32 v12, vcc, s34, v12
	s_add_u32 s0, s20, s8
	s_nop 0
	v_addc_co_u32_e32 v13, vcc, 0, v13, vcc
	global_load_dwordx4 v[50:53], v[12:13], off
	global_load_dwordx4 v[54:57], v[12:13], off offset:2048
	global_load_dwordx4 v[58:61], v[70:71], off offset:16
	global_load_dwordx4 v[62:65], v[74:75], off offset:16
	s_addc_u32 s1, s21, 0
	v_and_b32_e32 v12, 0xffe00000, v66
	v_lshrrev_b32_e32 v13, 5, v66
	v_and_b32_e32 v13, 0xe000, v13
	v_lshrrev_b32_e32 v14, 7, v66
	v_and_b32_e32 v14, 0x7c0, v14
	v_lshrrev_b32_e32 v15, 10, v66
	v_and_b32_e32 v15, 32, v15
	v_and_b32_e32 v16, 30, v8
	v_or3_b32 v12, v12, v13, v14
	v_or3_b32 v12, v12, v15, v16
	s_lshl_b32 s8, s8, 10
	v_add_u32_e32 v12, s8, v12
	v_xor_b32_e32 v16, 16, v12
	v_add_u32_e32 v14, 64, v12
	v_add_u32_e32 v18, 0xc0, v16
	v_add_u32_e32 v16, 0x80, v16
	v_xor_b32_e32 v13, 32, v12
	v_xor_b32_e32 v15, 32, v14
	v_xor_b32_e32 v17, 32, v16
	v_xor_b32_e32 v19, 32, v18
	s_add_i32 s39, s39, s22
	s_cmpk_lt_i32 s39, 0x1000
	s_waitcnt vmcnt(23)
	v_lshlrev_b32_e32 v8, 16, v82
	s_waitcnt vmcnt(22)
	v_lshlrev_b32_e32 v98, 16, v83
	s_waitcnt vmcnt(21)
	v_lshlrev_b32_e32 v99, 16, v84
	s_waitcnt vmcnt(20)
	v_lshlrev_b32_e32 v100, 16, v85
	s_waitcnt vmcnt(19)
	v_mov_b32_e32 v82, v34
	v_mov_b32_e32 v83, v35
	s_waitcnt vmcnt(18)
	v_mov_b32_e32 v84, v38
	v_mov_b32_e32 v85, v39
	s_waitcnt vmcnt(17)
	v_mov_b32_e32 v34, v42
	v_mov_b32_e32 v35, v43
	v_mul_f32_e32 v42, 0xbfb8aa3b, v8
	v_mul_f32_e32 v43, 0xbfb8aa3b, v98
	v_mov_b32_e32 v38, v36
	v_mov_b32_e32 v39, v37
	v_lshlrev_b32_e32 v66, 16, v68
	v_and_b32_e32 v67, 0xffff0000, v68
	v_lshlrev_b32_e32 v68, 16, v69
	v_and_b32_e32 v69, 0xffff0000, v69
	v_lshlrev_b32_e32 v70, 16, v72
	v_and_b32_e32 v71, 0xffff0000, v72
	v_lshlrev_b32_e32 v72, 16, v73
	v_and_b32_e32 v73, 0xffff0000, v73
	s_waitcnt vmcnt(16)
	v_mov_b32_e32 v36, v46
	v_mov_b32_e32 v37, v47
	v_mov_b32_e32 v46, v44
	v_mov_b32_e32 v47, v45
	v_exp_f32_e32 v103, v42
	v_exp_f32_e32 v107, v43
	v_mfma_f32_16x16x32_bf16 v[42:45], v[4:7], v[82:85], v[66:69]
	v_lshlrev_b32_e32 v74, 16, v76
	v_and_b32_e32 v75, 0xffff0000, v76
	v_lshlrev_b32_e32 v76, 16, v77
	v_and_b32_e32 v77, 0xffff0000, v77
	v_lshlrev_b32_e32 v78, 16, v80
	v_and_b32_e32 v79, 0xffff0000, v80
	v_lshlrev_b32_e32 v80, 16, v81
	v_and_b32_e32 v81, 0xffff0000, v81
	s_waitcnt vmcnt(15)
	v_lshlrev_b32_e32 v86, 16, v86
	s_waitcnt vmcnt(14)
	v_lshlrev_b32_e32 v87, 16, v87
	v_mul_f32_e32 v101, 0xbfb8aa3b, v99
	v_mfma_f32_16x16x32_bf16 v[38:41], v[4:7], v[38:41], v[70:73]
	s_waitcnt vmcnt(8)
	v_lshlrev_b32_e32 v93, 16, v93
	s_waitcnt vmcnt(7)
	v_lshlrev_b32_e32 v94, 16, v94
	v_mul_f32_e32 v104, 0xbfb8aa3b, v86
	v_mul_f32_e32 v105, 0xbfb8aa3b, v87
	v_exp_f32_e32 v67, v101
	v_mfma_f32_16x16x32_bf16 v[34:37], v[4:7], v[34:37], v[74:77]
	v_lshlrev_b32_e32 v88, 16, v88
	v_lshlrev_b32_e32 v89, 16, v89
	v_lshlrev_b32_e32 v90, 16, v90
	v_mfma_f32_16x16x32_bf16 v[4:7], v[4:7], v[46:49], v[78:81]
	v_lshlrev_b32_e32 v92, 16, v92
	s_waitcnt vmcnt(5)
	v_lshlrev_b32_e32 v96, 16, v96
	v_lshlrev_b32_e32 v95, 16, v95
	v_mul_f32_e32 v69, 0xbfb8aa3b, v93
	v_mul_f32_e32 v70, 0xbfb8aa3b, v94
	s_waitcnt vmcnt(3)
	v_mov_b32_e32 v46, v50
	v_mov_b32_e32 v47, v51
	s_waitcnt vmcnt(2)
	v_mov_b32_e32 v48, v54
	v_mov_b32_e32 v49, v55
	s_waitcnt vmcnt(1)
	v_mov_b32_e32 v50, v58
	v_mov_b32_e32 v51, v59
	v_exp_f32_e32 v58, v104
	v_exp_f32_e32 v59, v105
	v_lshlrev_b32_e32 v91, 16, v91
	v_mul_f32_e32 v102, 0xbfb8aa3b, v100
	v_lshlrev_b32_e32 v97, 16, v97
	v_mul_f32_e32 v106, 0xbfb8aa3b, v88
	v_mul_f32_e32 v108, 0xbfb8aa3b, v89
	v_mul_f32_e32 v109, 0xbfb8aa3b, v90
	v_mul_f32_e32 v68, 0xbfb8aa3b, v92
	v_mul_f32_e32 v72, 0xbfb8aa3b, v96
	v_mul_f32_e32 v73, 0xbfb8aa3b, v95
	v_mov_b32_e32 v54, v52
	v_mov_b32_e32 v55, v53
	v_mfma_f32_16x16x32_bf16 v[42:45], v[0:3], v[46:49], v[42:45]
	v_exp_f32_e32 v46, v69
	v_exp_f32_e32 v47, v70
	v_mul_f32_e32 v66, 0xbfb8aa3b, v91
	v_exp_f32_e32 v71, v102
	v_mul_f32_e32 v74, 0xbfb8aa3b, v97
	s_waitcnt vmcnt(0)
	v_mov_b32_e32 v52, v62
	v_mov_b32_e32 v53, v63
	v_mov_b32_e32 v62, v60
	v_mov_b32_e32 v63, v61
	v_exp_f32_e32 v60, v106
	v_exp_f32_e32 v61, v108
	v_exp_f32_e32 v75, v109
	v_exp_f32_e32 v68, v68
	v_exp_f32_e32 v48, v72
	v_mfma_f32_16x16x32_bf16 v[38:41], v[0:3], v[54:57], v[38:41]
	v_exp_f32_e32 v49, v73
	v_exp_f32_e32 v66, v66
	v_exp_f32_e32 v54, v74
	v_add_f32_e32 v55, 1.0, v103
	v_mfma_f32_16x16x32_bf16 v[34:37], v[0:3], v[50:53], v[34:37]
	v_add_f32_e32 v50, 1.0, v107
	v_add_f32_e32 v51, 1.0, v67
	v_add_f32_e32 v46, 1.0, v46
	v_mfma_f32_16x16x32_bf16 v[0:3], v[0:3], v[62:65], v[4:7]
	v_rcp_f32_e32 v62, v55
	v_add_f32_e32 v47, 1.0, v47
	v_add_f32_e32 v52, 1.0, v71
	v_add_f32_e32 v4, 1.0, v58
	v_add_f32_e32 v5, 1.0, v59
	v_rcp_f32_e32 v58, v50
	v_rcp_f32_e32 v59, v51
	v_add_f32_e32 v6, 1.0, v60
	v_add_f32_e32 v7, 1.0, v61
	v_add_f32_e32 v50, 1.0, v75
	v_add_f32_e32 v51, 1.0, v68
	v_add_f32_e32 v48, 1.0, v48
	v_add_f32_e32 v49, 1.0, v49
	v_rcp_f32_e32 v61, v4
	v_rcp_f32_e32 v63, v5
	v_rcp_f32_e32 v69, v46
	v_rcp_f32_e32 v70, v47
	v_mov_b32_e32 v4, v42
	v_mov_b32_e32 v5, v38
	v_mov_b32_e32 v46, v43
	v_mov_b32_e32 v47, v39
	v_add_f32_e32 v53, 1.0, v66
	v_rcp_f32_e32 v60, v52
	v_add_f32_e32 v52, 1.0, v54
	v_rcp_f32_e32 v64, v6
	v_rcp_f32_e32 v65, v7
	v_rcp_f32_e32 v66, v50
	v_rcp_f32_e32 v68, v51
	v_rcp_f32_e32 v71, v48
	v_rcp_f32_e32 v72, v49
	v_mov_b32_e32 v6, v34
	v_mov_b32_e32 v7, v0
	v_mov_b32_e32 v48, v35
	v_mov_b32_e32 v49, v1
	v_mov_b32_e32 v50, v44
	v_mov_b32_e32 v51, v40
	v_mov_b32_e32 v54, v45
	v_mov_b32_e32 v55, v41
	v_pk_mul_f32 v[4:5], v[4:5], v[4:5]
	v_pk_mul_f32 v[46:47], v[46:47], v[46:47]
	v_rcp_f32_e32 v67, v53
	v_rcp_f32_e32 v73, v52
	v_mov_b32_e32 v52, v36
	v_mov_b32_e32 v53, v2
	v_mov_b32_e32 v56, v37
	v_mov_b32_e32 v57, v3
	v_mul_f32_e32 v8, v62, v8
	v_mul_f32_e32 v62, v58, v98
	v_mul_f32_e32 v74, v59, v99
	v_pk_mul_f32 v[6:7], v[6:7], v[6:7]
	v_pk_mul_f32 v[48:49], v[48:49], v[48:49]
	v_pk_mul_f32 v[50:51], v[50:51], v[50:51]
	v_pk_mul_f32 v[54:55], v[54:55], v[54:55]
	v_mov_b32_e32 v58, v46
	v_mov_b32_e32 v59, v4
	v_mov_b32_e32 v4, v47
	v_pk_mul_f32 v[52:53], v[52:53], v[52:53]
	v_pk_mul_f32 v[56:57], v[56:57], v[56:57]
	v_mov_b32_e32 v46, v48
	v_mov_b32_e32 v47, v6
	v_mov_b32_e32 v6, v49
	v_mov_b32_e32 v48, v54
	v_mov_b32_e32 v49, v50
	v_mov_b32_e32 v50, v55
	v_pk_add_f32 v[4:5], v[58:59], v[4:5]
	v_mov_b32_e32 v54, v56
	v_mov_b32_e32 v55, v52
	v_pk_add_f32 v[48:49], v[48:49], v[50:51]
	v_pk_add_f32 v[4:5], v[4:5], v[46:47]
	v_mov_b32_e32 v52, v57
	v_pk_add_f32 v[46:47], v[48:49], v[54:55]
	v_pk_add_f32 v[4:5], v[4:5], v[6:7]
	v_pk_add_f32 v[6:7], v[46:47], v[52:53]
	ds_bpermute_b32 v47, v33, v5
	ds_bpermute_b32 v46, v33, v4
	ds_bpermute_b32 v49, v33, v7
	ds_bpermute_b32 v48, v33, v6
	v_mul_f32_e32 v60, v60, v100
	v_mul_f32_e32 v61, v61, v86
	s_waitcnt lgkmcnt(2)
	v_pk_add_f32 v[4:5], v[4:5], v[46:47]
	ds_bpermute_b32 v47, v32, v5
	s_waitcnt lgkmcnt(1)
	v_pk_add_f32 v[6:7], v[6:7], v[48:49]
	ds_bpermute_b32 v46, v32, v4
	ds_bpermute_b32 v33, v32, v7
	ds_bpermute_b32 v32, v32, v6
	v_mul_f32_e32 v63, v63, v87
	v_mul_f32_e32 v64, v64, v88
	s_waitcnt lgkmcnt(2)
	v_pk_add_f32 v[4:5], v[4:5], v[46:47]
	v_mul_f32_e32 v65, v65, v89
	s_waitcnt lgkmcnt(0)
	v_pk_add_f32 v[6:7], v[6:7], v[32:33]
	ds_bpermute_b32 v33, v31, v5
	ds_bpermute_b32 v32, v31, v4
	ds_bpermute_b32 v47, v31, v7
	ds_bpermute_b32 v46, v31, v6
	v_mul_f32_e32 v66, v66, v90
	v_mul_f32_e32 v67, v67, v91
	s_waitcnt lgkmcnt(2)
	v_pk_add_f32 v[4:5], v[4:5], v[32:33]
	ds_bpermute_b32 v33, v30, v5
	s_waitcnt lgkmcnt(1)
	v_pk_add_f32 v[6:7], v[6:7], v[46:47]
	ds_bpermute_b32 v32, v30, v4
	ds_bpermute_b32 v31, v30, v7
	ds_bpermute_b32 v30, v30, v6
	v_mul_f32_e32 v68, v68, v92
	v_mul_f32_e32 v69, v69, v93
	s_waitcnt lgkmcnt(2)
	v_pk_add_f32 v[4:5], v[4:5], v[32:33]
	v_mul_f32_e32 v70, v70, v94
	s_waitcnt lgkmcnt(0)
	v_pk_add_f32 v[6:7], v[6:7], v[30:31]
	v_pk_fma_f32 v[4:5], v[4:5], s[14:15], v[10:11] op_sel_hi:[1,0,0]
	v_pk_fma_f32 v[6:7], v[6:7], s[14:15], v[10:11] op_sel_hi:[1,0,0]
	v_mul_f32_e32 v30, 0x4b800000, v5
	v_cmp_gt_f32_e64 s[6:7], s35, v5
	v_mul_f32_e32 v31, 0x4b800000, v4
	v_cmp_gt_f32_e32 vcc, s35, v4
	v_mul_f32_e32 v32, 0x4b800000, v7
	v_mul_f32_e32 v33, 0x4b800000, v6
	v_cmp_gt_f32_e64 s[0:1], s35, v6
	v_cmp_gt_f32_e64 s[4:5], s35, v7
	v_cndmask_b32_e64 v5, v5, v30, s[6:7]
	v_cndmask_b32_e32 v4, v4, v31, vcc
	v_cndmask_b32_e64 v7, v7, v32, s[4:5]
	v_cndmask_b32_e64 v6, v6, v33, s[0:1]
	v_rsq_f32_e32 v5, v5
	v_rsq_f32_e32 v4, v4
	v_rsq_f32_e32 v7, v7
	v_rsq_f32_e32 v6, v6
	v_mul_f32_e32 v30, 0x45800000, v5
	v_mul_f32_e32 v31, 0x45800000, v4
	v_mul_f32_e32 v32, 0x45800000, v7
	v_mul_f32_e32 v33, 0x45800000, v6
	v_cndmask_b32_e64 v5, v5, v30, s[6:7]
	v_cndmask_b32_e32 v4, v4, v31, vcc
	v_cndmask_b32_e64 v7, v7, v32, s[4:5]
	v_cndmask_b32_e64 v6, v6, v33, s[0:1]
	v_mul_f32_e32 v30, v42, v5
	v_mul_f32_e32 v31, v43, v4
	v_mul_f32_e32 v32, v44, v7
	v_mul_f32_e32 v33, v45, v6
	v_mul_f32_e32 v38, v38, v5
	v_mul_f32_e32 v39, v39, v4
	v_mul_f32_e32 v40, v40, v7
	v_mul_f32_e32 v41, v41, v6
	v_mul_f32_e32 v34, v34, v5
	v_mul_f32_e32 v35, v35, v4
	v_mul_f32_e32 v36, v36, v7
	v_mul_f32_e32 v37, v37, v6
	v_mul_f32_e32 v0, v0, v5
	v_mul_f32_e32 v1, v1, v4
	v_mul_f32_e32 v2, v2, v7
	v_mul_f32_e32 v3, v3, v6
	v_mul_f32_e32 v4, v29, v30
	v_mul_f32_e32 v71, v71, v96
	v_mul_f32_e32 v72, v72, v95
	v_mul_f32_e32 v73, v73, v97
	v_mul_f32_e32 v5, v29, v31
	v_mul_f32_e32 v6, v29, v32
	v_mul_f32_e32 v7, v29, v33
	v_mul_f32_e32 v29, v28, v38
	v_mul_f32_e32 v30, v28, v39
	v_mul_f32_e32 v31, v28, v40
	v_mul_f32_e32 v28, v28, v41
	v_mul_f32_e32 v32, v27, v34
	v_mul_f32_e32 v33, v27, v35
	v_mul_f32_e32 v34, v27, v36
	v_mul_f32_e32 v27, v27, v37
	v_mul_f32_e32 v0, v26, v0
	v_mul_f32_e32 v1, v26, v1
	v_mul_f32_e32 v2, v26, v2
	v_mul_f32_e32 v3, v26, v3
	v_mul_f32_e32 v4, v8, v4
	v_mul_f32_e32 v5, v61, v5
	v_mul_f32_e32 v6, v63, v6
	v_mul_f32_e32 v7, v64, v7
	v_mul_f32_e32 v8, v62, v29
	v_mul_f32_e32 v26, v65, v30
	v_mul_f32_e32 v29, v66, v31
	v_mul_f32_e32 v28, v67, v28
	v_mul_f32_e32 v30, v74, v32
	v_mul_f32_e32 v31, v68, v33
	v_mul_f32_e32 v32, v69, v34
	v_mul_f32_e32 v27, v70, v27
	v_mul_f32_e32 v0, v60, v0
	v_mul_f32_e32 v1, v71, v1
	v_mul_f32_e32 v2, v72, v2
	v_mul_f32_e32 v3, v73, v3
	v_cvt_pk_bf16_f32 v4, v4, s0
	v_cvt_pk_bf16_f32 v5, v5, s0
	v_cvt_pk_bf16_f32 v6, v6, s0
	v_cvt_pk_bf16_f32 v7, v7, s0
	v_cvt_pk_bf16_f32 v8, v8, s0
	v_cvt_pk_bf16_f32 v26, v26, s0
	v_cvt_pk_bf16_f32 v29, v29, s0
	v_cvt_pk_bf16_f32 v28, v28, s0
	v_cvt_pk_bf16_f32 v30, v30, s0
	v_cvt_pk_bf16_f32 v31, v31, s0
	v_cvt_pk_bf16_f32 v32, v32, s0
	v_cvt_pk_bf16_f32 v27, v27, s0
	v_cvt_pk_bf16_f32 v0, v0, s0
	v_cvt_pk_bf16_f32 v1, v1, s0
	v_cvt_pk_bf16_f32 v2, v2, s0
	v_cvt_pk_bf16_f32 v3, v3, s0
	global_store_short v12, v4, s[20:21]
	global_store_short v14, v5, s[20:21]
	global_store_short v16, v6, s[20:21]
	global_store_short v18, v7, s[20:21]
	global_store_short v13, v8, s[20:21]
	global_store_short v15, v26, s[20:21]
	global_store_short v17, v29, s[20:21]
	global_store_short v19, v28, s[20:21]
	global_store_short v12, v30, s[100:101]
	global_store_short v14, v31, s[100:101]
	global_store_short v16, v32, s[100:101]
	global_store_short v18, v27, s[100:101]
	global_store_short v13, v0, s[100:101]
	global_store_short v15, v1, s[100:101]
	global_store_short v17, v2, s[100:101]
	global_store_short v19, v3, s[100:101]
	s_cbranch_scc1 .LBB0_1031

.LBB0_1094:
	s_ashr_i32 s4, s70, 2
	v_and_b32_e32 v0, 63, v181
	s_cmpk_gt_i32 s4, 0x1ff
	s_cselect_b64 s[0:1], -1, 0
	v_ashrrev_i32_e32 v1, 6, v181
	s_cmpk_lt_i32 s4, 0x200
	s_cselect_b64 s[24:25], -1, 0
	v_cmp_gt_i32_e32 vcc, 1, v1
	s_nop 1
	s_or_b64 s[42:43], s[24:25], vcc
	s_lshl_b32 s5, s4, 4
	s_addk_i32 s5, 0x6000
	s_lshl_b32 s6, s4, 6
	s_and_b64 s[0:1], s[0:1], exec
	s_cselect_b32 s0, s5, s6
	s_and_b32 s5, s70, 0xfffffe00
	s_bfe_u32 s6, s70, 0x70002
	s_and_b32 s1, s60, 0x180
	s_or_b32 s5, s6, s5
	s_or_b32 s5, s5, s1
	s_lshr_b32 s98, s4, 2
	s_lshl_b32 s98, s98, 21
	s_and_b32 s99, s4, 3
	s_lshl_b32 s99, s99, 14
	s_or_b32 s98, s98, s99
	s_lshl_b32 s99, s1, 11
	s_add_u32 s98, s98, s99
	s_add_u32 s98, s98, 0x100000
	s_cmpk_lt_i32 s4, 0x200
	s_cselect_b64 s[100:101], -1, 0
	s_cselect_b32 s99, 0x10000, 64
	s_cmpk_lt_i32 s4, 0x200
	s_cselect_b32 s4, s5, s70
	s_ashr_i32 s5, s4, 31
	s_lshl_b64 s[24:25], s[4:5], 14
	s_add_u32 s30, s46, s24
	s_addc_u32 s31, s47, s25
	s_add_u32 s24, s56, s24
	s_addc_u32 s25, s57, s25
	s_lshl_b64 s[4:5], s[4:5], 15
	s_add_u32 s4, s58, s4
	s_addc_u32 s5, s59, s5
	v_and_b32_e32 v2, 15, v181
	v_bfe_u32 v3, v181, 4, 2
	v_lshlrev_b32_e32 v4, 3, v0
	v_lshl_add_u32 v4, v1, 12, v4
	v_lshl_add_u32 v5, v1, 4, v2
	v_lshlrev_b32_e32 v5, 8, v5
	v_lshl_add_u32 v5, v3, 4, v5
	v_lshlrev_b32_e32 v6, 4, v181
	v_add_u32_e32 v7, 0x1000, v6
	v_add_u32_e32 v8, 0x2000, v6
	v_add_u32_e32 v9, 0x3000, v6
	v_add_u32_e32 v10, 0x4000, v6
	v_add_u32_e32 v11, 0x5000, v6
	v_add_u32_e32 v12, 0x6000, v6
	v_add_u32_e32 v13, 0x7000, v6
	v_lshrrev_b32_e32 v16, 4, v181
	v_mul_u32_u24_e32 v16, 272, v16
	v_lshl_add_u32 v16, v2, 4, v16
	v_mul_u32_u24_e32 v233, 272, v2
	v_lshl_add_u32 v233, v3, 4, v233
	v_lshl_add_u32 v14, v1, 4, s0
	v_add_u32_e32 v14, v14, v2
	v_lshlrev_b32_e32 v14, 13, v14
	v_lshlrev_b32_e32 v15, 3, v3
	v_add_u32_e32 v14, v14, v15
	s_lshl_b32 s6, s1, 1
	s_add_i32 s6, s6, 0x400
	v_add_u32_e32 v232, s6, v14
	v_add_u32_e32 v14, 0x1800, v232
	v_lshrrev_b32_e32 v234, 1, v1
	v_lshlrev_b32_e32 v234, 13, v234
	v_and_b32_e32 v235, 1, v1
	v_lshl_or_b32 v234, v235, 10, v234
	v_lshl_or_b32 v234, v2, 6, v234
	v_lshrrev_b32_e32 v235, 1, v3
	v_bfe_u32 v236, v2, 1, 2
	v_xor_b32_e32 v235, v235, v236
	v_lshl_or_b32 v234, v235, 4, v234
	v_and_b32_e32 v235, 1, v3
	v_lshl_or_b32 v234, v235, 3, v234
	v_add_u32_e32 v234, s98, v234
	v_cndmask_b32_e64 v232, v232, v234, s[100:101]
	v_xor_b32_e32 v234, 32, v232
	global_load_dwordx2 v[62:63], v4, s[30:31]
	global_load_dwordx2 v[64:65], v4, s[30:31] offset:512
	global_load_dwordx2 v[66:67], v4, s[30:31] offset:1024
	global_load_dwordx2 v[68:69], v4, s[30:31] offset:1536
	global_load_dwordx2 v[70:71], v4, s[30:31] offset:2048
	global_load_dwordx2 v[72:73], v4, s[30:31] offset:2560
	global_load_dwordx2 v[74:75], v4, s[30:31] offset:3072
	global_load_dwordx2 v[76:77], v4, s[30:31] offset:3584
	global_load_dwordx4 v[46:49], v5, s[24:25]
	global_load_dwordx4 v[50:53], v5, s[24:25] offset:64
	global_load_dwordx4 v[54:57], v5, s[24:25] offset:128
	global_load_dwordx4 v[58:61], v5, s[24:25] offset:192
	global_load_dwordx2 v[216:217], v14, s[20:21]
	global_load_dwordx2 v[218:219], v14, s[20:21] offset:32
	global_load_dwordx2 v[220:221], v14, s[20:21] offset:64
	global_load_dwordx2 v[222:223], v14, s[20:21] offset:96
	global_load_dwordx2 v[224:225], v14, s[20:21] offset:128
	global_load_dwordx2 v[226:227], v14, s[20:21] offset:160
	global_load_dwordx2 v[228:229], v14, s[20:21] offset:192
	global_load_dwordx2 v[230:231], v14, s[20:21] offset:224
	global_load_dwordx4 v[78:81], v6, s[4:5]
	global_load_dwordx4 v[82:85], v7, s[4:5]
	global_load_dwordx4 v[86:89], v8, s[4:5]
	global_load_dwordx4 v[90:93], v9, s[4:5]
	global_load_dwordx4 v[94:97], v10, s[4:5]
	global_load_dwordx4 v[98:101], v11, s[4:5]
	global_load_dwordx4 v[102:105], v12, s[4:5]
	global_load_dwordx4 v[106:109], v13, s[4:5]
	s_barrier
	s_waitcnt vmcnt(0)
	ds_write_b128 v16, v[78:81]
	ds_write_b128 v16, v[82:85] offset:4352
	ds_write_b128 v16, v[86:89] offset:8704
	ds_write_b128 v16, v[90:93] offset:13056
	ds_write_b128 v16, v[94:97] offset:17408
	ds_write_b128 v16, v[98:101] offset:21760
	ds_write_b128 v16, v[102:105] offset:26112
	ds_write_b128 v16, v[106:109] offset:30464
	s_waitcnt lgkmcnt(0)
	s_barrier
	s_mov_b64 vcc, s[42:43]
	s_and_saveexec_b64 s[42:43], vcc
	s_cbranch_execz .LBB0_1087
	v_lshlrev_b32_e32 v28, 16, v62
	v_and_b32_e32 v29, 0xffff0000, v62
	v_lshlrev_b32_e32 v30, 16, v63
	v_and_b32_e32 v31, 0xffff0000, v63
	v_lshlrev_b32_e32 v24, 16, v64
	v_and_b32_e32 v25, 0xffff0000, v64
	v_lshlrev_b32_e32 v26, 16, v65
	v_and_b32_e32 v27, 0xffff0000, v65
	v_lshlrev_b32_e32 v20, 16, v66
	v_and_b32_e32 v21, 0xffff0000, v66
	v_lshlrev_b32_e32 v22, 16, v67
	v_and_b32_e32 v23, 0xffff0000, v67
	v_lshlrev_b32_e32 v16, 16, v68
	v_and_b32_e32 v17, 0xffff0000, v68
	v_lshlrev_b32_e32 v18, 16, v69
	v_and_b32_e32 v19, 0xffff0000, v69
	v_lshlrev_b32_e32 v12, 16, v70
	v_and_b32_e32 v13, 0xffff0000, v70
	v_lshlrev_b32_e32 v14, 16, v71
	v_and_b32_e32 v15, 0xffff0000, v71
	v_lshlrev_b32_e32 v8, 16, v72
	v_and_b32_e32 v9, 0xffff0000, v72
	v_lshlrev_b32_e32 v10, 16, v73
	v_and_b32_e32 v11, 0xffff0000, v73
	v_lshlrev_b32_e32 v4, 16, v74
	v_and_b32_e32 v5, 0xffff0000, v74
	v_lshlrev_b32_e32 v6, 16, v75
	v_and_b32_e32 v7, 0xffff0000, v75
	v_lshlrev_b32_e32 v0, 16, v76
	v_and_b32_e32 v1, 0xffff0000, v76
	v_lshlrev_b32_e32 v2, 16, v77
	v_and_b32_e32 v3, 0xffff0000, v77
	ds_read_b128 v[78:81], v233 offset:0
	ds_read_b128 v[82:85], v233 offset:4352
	ds_read_b128 v[86:89], v233 offset:8704
	ds_read_b128 v[90:93], v233 offset:13056
	ds_read_b128 v[94:97], v233 offset:17408
	ds_read_b128 v[98:101], v233 offset:21760
	ds_read_b128 v[102:105], v233 offset:26112
	ds_read_b128 v[106:109], v233 offset:30464
	s_waitcnt lgkmcnt(4)
	ds_read_b128 v[110:113], v233 offset:64
	ds_read_b128 v[114:117], v233 offset:4416
	ds_read_b128 v[118:121], v233 offset:8768
	ds_read_b128 v[122:125], v233 offset:13120
	ds_read_b128 v[126:129], v233 offset:17472
	ds_read_b128 v[130:133], v233 offset:21824
	ds_read_b128 v[134:137], v233 offset:26176
	ds_read_b128 v[138:141], v233 offset:30528
	s_waitcnt lgkmcnt(8)
	v_mfma_f32_16x16x32_bf16 v[28:31], v[78:81], v[46:49], v[28:31]
	v_mfma_f32_16x16x32_bf16 v[24:27], v[82:85], v[46:49], v[24:27]
	v_mfma_f32_16x16x32_bf16 v[20:23], v[86:89], v[46:49], v[20:23]
	v_mfma_f32_16x16x32_bf16 v[16:19], v[90:93], v[46:49], v[16:19]
	v_mfma_f32_16x16x32_bf16 v[12:15], v[94:97], v[46:49], v[12:15]
	v_mfma_f32_16x16x32_bf16 v[8:11], v[98:101], v[46:49], v[8:11]
	v_mfma_f32_16x16x32_bf16 v[4:7], v[102:105], v[46:49], v[4:7]
	v_mfma_f32_16x16x32_bf16 v[0:3], v[106:109], v[46:49], v[0:3]
	s_waitcnt lgkmcnt(4)
	ds_read_b128 v[78:81], v233 offset:128
	ds_read_b128 v[82:85], v233 offset:4480
	ds_read_b128 v[86:89], v233 offset:8832
	ds_read_b128 v[90:93], v233 offset:13184
	ds_read_b128 v[94:97], v233 offset:17536
	ds_read_b128 v[98:101], v233 offset:21888
	ds_read_b128 v[102:105], v233 offset:26240
	ds_read_b128 v[106:109], v233 offset:30592
	s_waitcnt lgkmcnt(8)
	v_mfma_f32_16x16x32_bf16 v[28:31], v[110:113], v[50:53], v[28:31]
	v_mfma_f32_16x16x32_bf16 v[24:27], v[114:117], v[50:53], v[24:27]
	v_mfma_f32_16x16x32_bf16 v[20:23], v[118:121], v[50:53], v[20:23]
	v_mfma_f32_16x16x32_bf16 v[16:19], v[122:125], v[50:53], v[16:19]
	v_mfma_f32_16x16x32_bf16 v[12:15], v[126:129], v[50:53], v[12:15]
	v_mfma_f32_16x16x32_bf16 v[8:11], v[130:133], v[50:53], v[8:11]
	v_mfma_f32_16x16x32_bf16 v[4:7], v[134:137], v[50:53], v[4:7]
	v_mfma_f32_16x16x32_bf16 v[0:3], v[138:141], v[50:53], v[0:3]
	s_waitcnt lgkmcnt(4)
	ds_read_b128 v[110:113], v233 offset:192
	ds_read_b128 v[114:117], v233 offset:4544
	ds_read_b128 v[118:121], v233 offset:8896
	ds_read_b128 v[122:125], v233 offset:13248
	ds_read_b128 v[126:129], v233 offset:17600
	ds_read_b128 v[130:133], v233 offset:21952
	ds_read_b128 v[134:137], v233 offset:26304
	ds_read_b128 v[138:141], v233 offset:30656
	s_waitcnt lgkmcnt(8)
	v_mfma_f32_16x16x32_bf16 v[28:31], v[78:81], v[54:57], v[28:31]
	v_mfma_f32_16x16x32_bf16 v[24:27], v[82:85], v[54:57], v[24:27]
	v_mfma_f32_16x16x32_bf16 v[20:23], v[86:89], v[54:57], v[20:23]
	v_mfma_f32_16x16x32_bf16 v[16:19], v[90:93], v[54:57], v[16:19]
	v_mfma_f32_16x16x32_bf16 v[12:15], v[94:97], v[54:57], v[12:15]
	v_mfma_f32_16x16x32_bf16 v[8:11], v[98:101], v[54:57], v[8:11]
	v_mfma_f32_16x16x32_bf16 v[4:7], v[102:105], v[54:57], v[4:7]
	v_mfma_f32_16x16x32_bf16 v[0:3], v[106:109], v[54:57], v[0:3]
	s_waitcnt lgkmcnt(0)
	v_mfma_f32_16x16x32_bf16 v[28:31], v[110:113], v[58:61], v[28:31]
	v_mfma_f32_16x16x32_bf16 v[24:27], v[114:117], v[58:61], v[24:27]
	v_mfma_f32_16x16x32_bf16 v[20:23], v[118:121], v[58:61], v[20:23]
	v_mfma_f32_16x16x32_bf16 v[16:19], v[122:125], v[58:61], v[16:19]
	v_mfma_f32_16x16x32_bf16 v[12:15], v[126:129], v[58:61], v[12:15]
	v_mfma_f32_16x16x32_bf16 v[8:11], v[130:133], v[58:61], v[8:11]
	v_mfma_f32_16x16x32_bf16 v[4:7], v[134:137], v[58:61], v[4:7]
	v_mfma_f32_16x16x32_bf16 v[0:3], v[138:141], v[58:61], v[0:3]
	v_xor_b32_e32 v241, 16, v40
	v_xor_b32_e32 v242, 32, v40
	v_lshlrev_b32_e32 v241, 2, v241
	v_lshlrev_b32_e32 v242, 2, v242
	s_nop 4
	v_mul_f32_e32 v46, v28, v28
	v_fmac_f32_e32 v46, v29, v29
	v_fmac_f32_e32 v46, v30, v30
	v_fmac_f32_e32 v46, v31, v31
	v_fmac_f32_e32 v46, v24, v24
	v_fmac_f32_e32 v46, v25, v25
	v_fmac_f32_e32 v46, v26, v26
	v_fmac_f32_e32 v46, v27, v27
	v_fmac_f32_e32 v46, v20, v20
	v_fmac_f32_e32 v46, v21, v21
	v_fmac_f32_e32 v46, v22, v22
	v_fmac_f32_e32 v46, v23, v23
	v_fmac_f32_e32 v46, v16, v16
	v_fmac_f32_e32 v46, v17, v17
	v_fmac_f32_e32 v46, v18, v18
	v_fmac_f32_e32 v46, v19, v19
	v_fmac_f32_e32 v46, v12, v12
	v_fmac_f32_e32 v46, v13, v13
	v_fmac_f32_e32 v46, v14, v14
	v_fmac_f32_e32 v46, v15, v15
	v_fmac_f32_e32 v46, v8, v8
	v_fmac_f32_e32 v46, v9, v9
	v_fmac_f32_e32 v46, v10, v10
	v_fmac_f32_e32 v46, v11, v11
	v_fmac_f32_e32 v46, v4, v4
	v_fmac_f32_e32 v46, v5, v5
	v_fmac_f32_e32 v46, v6, v6
	v_fmac_f32_e32 v46, v7, v7
	v_fmac_f32_e32 v46, v0, v0
	v_fmac_f32_e32 v46, v1, v1
	v_fmac_f32_e32 v46, v2, v2
	v_fmac_f32_e32 v46, v3, v3
	ds_bpermute_b32 v47, v241, v46
	s_waitcnt lgkmcnt(0)
	v_add_f32_e32 v46, v46, v47
	ds_bpermute_b32 v47, v242, v46
	s_waitcnt lgkmcnt(0)
	v_add_f32_e32 v46, v46, v47
	v_mov_b32_e32 v50, 0x358637bd
	v_fmamk_f32 v46, v46, 0x3c000000, v50
	v_rsq_f32_e32 v46, v46
	v_lshlrev_b32_e32 v48, 16, v216
	v_and_b32_e32 v49, 0xffff0000, v216
	v_lshlrev_b32_e32 v50, 16, v217
	v_and_b32_e32 v51, 0xffff0000, v217
	v_mul_f32_e32 v52, 0xbfb8aa3b, v48
	v_mul_f32_e32 v53, 0xbfb8aa3b, v49
	v_mul_f32_e32 v54, 0xbfb8aa3b, v50
	v_mul_f32_e32 v55, 0xbfb8aa3b, v51
	v_exp_f32_e32 v52, v52
	v_exp_f32_e32 v53, v53
	v_exp_f32_e32 v54, v54
	v_exp_f32_e32 v55, v55
	v_mul_f32_e32 v56, v28, v46
	v_mul_f32_e32 v57, v29, v46
	v_mul_f32_e32 v58, v30, v46
	v_mul_f32_e32 v59, v31, v46
	v_add_f32_e32 v52, 1.0, v52
	v_add_f32_e32 v53, 1.0, v53
	v_add_f32_e32 v54, 1.0, v54
	v_add_f32_e32 v55, 1.0, v55
	v_rcp_f32_e32 v52, v52
	v_rcp_f32_e32 v53, v53
	v_rcp_f32_e32 v54, v54
	v_rcp_f32_e32 v55, v55
	v_mul_f32_e32 v56, v184, v56
	v_mul_f32_e32 v57, v185, v57
	v_mul_f32_e32 v58, v186, v58
	v_mul_f32_e32 v59, v187, v59
	v_mul_f32_e32 v52, v52, v48
	v_mul_f32_e32 v53, v53, v49
	v_mul_f32_e32 v54, v54, v50
	v_mul_f32_e32 v55, v55, v51
	v_mul_f32_e32 v56, v52, v56
	v_mul_f32_e32 v57, v53, v57
	v_mul_f32_e32 v58, v54, v58
	v_mul_f32_e32 v59, v55, v59
	v_cvt_pk_bf16_f32 v60, v56, v57
	v_cvt_pk_bf16_f32 v61, v58, v59
	s_mov_b64 s[24:25], s[20:21]
	global_store_dwordx2 v232, v[60:61], s[24:25]
	v_lshlrev_b32_e32 v48, 16, v218
	v_and_b32_e32 v49, 0xffff0000, v218
	v_lshlrev_b32_e32 v50, 16, v219
	v_and_b32_e32 v51, 0xffff0000, v219
	v_mul_f32_e32 v52, 0xbfb8aa3b, v48
	v_mul_f32_e32 v53, 0xbfb8aa3b, v49
	v_mul_f32_e32 v54, 0xbfb8aa3b, v50
	v_mul_f32_e32 v55, 0xbfb8aa3b, v51
	v_exp_f32_e32 v52, v52
	v_exp_f32_e32 v53, v53
	v_exp_f32_e32 v54, v54
	v_exp_f32_e32 v55, v55
	v_mul_f32_e32 v56, v24, v46
	v_mul_f32_e32 v57, v25, v46
	v_mul_f32_e32 v58, v26, v46
	v_mul_f32_e32 v59, v27, v46
	v_add_f32_e32 v52, 1.0, v52
	v_add_f32_e32 v53, 1.0, v53
	v_add_f32_e32 v54, 1.0, v54
	v_add_f32_e32 v55, 1.0, v55
	v_rcp_f32_e32 v52, v52
	v_rcp_f32_e32 v53, v53
	v_rcp_f32_e32 v54, v54
	v_rcp_f32_e32 v55, v55
	v_mul_f32_e32 v56, v188, v56
	v_mul_f32_e32 v57, v189, v57
	v_mul_f32_e32 v58, v190, v58
	v_mul_f32_e32 v59, v191, v59
	v_mul_f32_e32 v52, v52, v48
	v_mul_f32_e32 v53, v53, v49
	v_mul_f32_e32 v54, v54, v50
	v_mul_f32_e32 v55, v55, v51
	v_mul_f32_e32 v56, v52, v56
	v_mul_f32_e32 v57, v53, v57
	v_mul_f32_e32 v58, v54, v58
	v_mul_f32_e32 v59, v55, v59
	v_cvt_pk_bf16_f32 v60, v56, v57
	v_cvt_pk_bf16_f32 v61, v58, v59
	global_store_dwordx2 v234, v[60:61], s[24:25]
	v_lshlrev_b32_e32 v48, 16, v220
	v_and_b32_e32 v49, 0xffff0000, v220
	v_lshlrev_b32_e32 v50, 16, v221
	v_and_b32_e32 v51, 0xffff0000, v221
	v_mul_f32_e32 v52, 0xbfb8aa3b, v48
	v_mul_f32_e32 v53, 0xbfb8aa3b, v49
	v_mul_f32_e32 v54, 0xbfb8aa3b, v50
	v_mul_f32_e32 v55, 0xbfb8aa3b, v51
	v_exp_f32_e32 v52, v52
	v_exp_f32_e32 v53, v53
	v_exp_f32_e32 v54, v54
	v_exp_f32_e32 v55, v55
	v_mul_f32_e32 v56, v20, v46
	v_mul_f32_e32 v57, v21, v46
	v_mul_f32_e32 v58, v22, v46
	v_mul_f32_e32 v59, v23, v46
	v_add_f32_e32 v52, 1.0, v52
	v_add_f32_e32 v53, 1.0, v53
	v_add_f32_e32 v54, 1.0, v54
	v_add_f32_e32 v55, 1.0, v55
	v_rcp_f32_e32 v52, v52
	v_rcp_f32_e32 v53, v53
	v_rcp_f32_e32 v54, v54
	v_rcp_f32_e32 v55, v55
	v_mul_f32_e32 v56, v192, v56
	v_mul_f32_e32 v57, v193, v57
	v_mul_f32_e32 v58, v194, v58
	v_mul_f32_e32 v59, v195, v59
	v_mul_f32_e32 v52, v52, v48
	v_mul_f32_e32 v53, v53, v49
	v_mul_f32_e32 v54, v54, v50
	v_mul_f32_e32 v55, v55, v51
	v_mul_f32_e32 v56, v52, v56
	v_mul_f32_e32 v57, v53, v57
	v_mul_f32_e32 v58, v54, v58
	v_mul_f32_e32 v59, v55, v59
	v_cvt_pk_bf16_f32 v60, v56, v57
	v_cvt_pk_bf16_f32 v61, v58, v59
	s_add_u32 s24, s24, s99
	s_addc_u32 s25, s25, 0
	global_store_dwordx2 v232, v[60:61], s[24:25]
	v_lshlrev_b32_e32 v48, 16, v222
	v_and_b32_e32 v49, 0xffff0000, v222
	v_lshlrev_b32_e32 v50, 16, v223
	v_and_b32_e32 v51, 0xffff0000, v223
	v_mul_f32_e32 v52, 0xbfb8aa3b, v48
	v_mul_f32_e32 v53, 0xbfb8aa3b, v49
	v_mul_f32_e32 v54, 0xbfb8aa3b, v50
	v_mul_f32_e32 v55, 0xbfb8aa3b, v51
	v_exp_f32_e32 v52, v52
	v_exp_f32_e32 v53, v53
	v_exp_f32_e32 v54, v54
	v_exp_f32_e32 v55, v55
	v_mul_f32_e32 v56, v16, v46
	v_mul_f32_e32 v57, v17, v46
	v_mul_f32_e32 v58, v18, v46
	v_mul_f32_e32 v59, v19, v46
	v_add_f32_e32 v52, 1.0, v52
	v_add_f32_e32 v53, 1.0, v53
	v_add_f32_e32 v54, 1.0, v54
	v_add_f32_e32 v55, 1.0, v55
	v_rcp_f32_e32 v52, v52
	v_rcp_f32_e32 v53, v53
	v_rcp_f32_e32 v54, v54
	v_rcp_f32_e32 v55, v55
	v_mul_f32_e32 v56, v196, v56
	v_mul_f32_e32 v57, v197, v57
	v_mul_f32_e32 v58, v198, v58
	v_mul_f32_e32 v59, v199, v59
	v_mul_f32_e32 v52, v52, v48
	v_mul_f32_e32 v53, v53, v49
	v_mul_f32_e32 v54, v54, v50
	v_mul_f32_e32 v55, v55, v51
	v_mul_f32_e32 v56, v52, v56
	v_mul_f32_e32 v57, v53, v57
	v_mul_f32_e32 v58, v54, v58
	v_mul_f32_e32 v59, v55, v59
	v_cvt_pk_bf16_f32 v60, v56, v57
	v_cvt_pk_bf16_f32 v61, v58, v59
	global_store_dwordx2 v234, v[60:61], s[24:25]
	v_lshlrev_b32_e32 v48, 16, v224
	v_and_b32_e32 v49, 0xffff0000, v224
	v_lshlrev_b32_e32 v50, 16, v225
	v_and_b32_e32 v51, 0xffff0000, v225
	v_mul_f32_e32 v52, 0xbfb8aa3b, v48
	v_mul_f32_e32 v53, 0xbfb8aa3b, v49
	v_mul_f32_e32 v54, 0xbfb8aa3b, v50
	v_mul_f32_e32 v55, 0xbfb8aa3b, v51
	v_exp_f32_e32 v52, v52
	v_exp_f32_e32 v53, v53
	v_exp_f32_e32 v54, v54
	v_exp_f32_e32 v55, v55
	v_mul_f32_e32 v56, v12, v46
	v_mul_f32_e32 v57, v13, v46
	v_mul_f32_e32 v58, v14, v46
	v_mul_f32_e32 v59, v15, v46
	v_add_f32_e32 v52, 1.0, v52
	v_add_f32_e32 v53, 1.0, v53
	v_add_f32_e32 v54, 1.0, v54
	v_add_f32_e32 v55, 1.0, v55
	v_rcp_f32_e32 v52, v52
	v_rcp_f32_e32 v53, v53
	v_rcp_f32_e32 v54, v54
	v_rcp_f32_e32 v55, v55
	v_mul_f32_e32 v56, v200, v56
	v_mul_f32_e32 v57, v201, v57
	v_mul_f32_e32 v58, v202, v58
	v_mul_f32_e32 v59, v203, v59
	v_mul_f32_e32 v52, v52, v48
	v_mul_f32_e32 v53, v53, v49
	v_mul_f32_e32 v54, v54, v50
	v_mul_f32_e32 v55, v55, v51
	v_mul_f32_e32 v56, v52, v56
	v_mul_f32_e32 v57, v53, v57
	v_mul_f32_e32 v58, v54, v58
	v_mul_f32_e32 v59, v55, v59
	v_cvt_pk_bf16_f32 v60, v56, v57
	v_cvt_pk_bf16_f32 v61, v58, v59
	s_add_u32 s24, s24, s99
	s_addc_u32 s25, s25, 0
	global_store_dwordx2 v232, v[60:61], s[24:25]
	v_lshlrev_b32_e32 v48, 16, v226
	v_and_b32_e32 v49, 0xffff0000, v226
	v_lshlrev_b32_e32 v50, 16, v227
	v_and_b32_e32 v51, 0xffff0000, v227
	v_mul_f32_e32 v52, 0xbfb8aa3b, v48
	v_mul_f32_e32 v53, 0xbfb8aa3b, v49
	v_mul_f32_e32 v54, 0xbfb8aa3b, v50
	v_mul_f32_e32 v55, 0xbfb8aa3b, v51
	v_exp_f32_e32 v52, v52
	v_exp_f32_e32 v53, v53
	v_exp_f32_e32 v54, v54
	v_exp_f32_e32 v55, v55
	v_mul_f32_e32 v56, v8, v46
	v_mul_f32_e32 v57, v9, v46
	v_mul_f32_e32 v58, v10, v46
	v_mul_f32_e32 v59, v11, v46
	v_add_f32_e32 v52, 1.0, v52
	v_add_f32_e32 v53, 1.0, v53
	v_add_f32_e32 v54, 1.0, v54
	v_add_f32_e32 v55, 1.0, v55
	v_rcp_f32_e32 v52, v52
	v_rcp_f32_e32 v53, v53
	v_rcp_f32_e32 v54, v54
	v_rcp_f32_e32 v55, v55
	v_mul_f32_e32 v56, v204, v56
	v_mul_f32_e32 v57, v205, v57
	v_mul_f32_e32 v58, v206, v58
	v_mul_f32_e32 v59, v207, v59
	v_mul_f32_e32 v52, v52, v48
	v_mul_f32_e32 v53, v53, v49
	v_mul_f32_e32 v54, v54, v50
	v_mul_f32_e32 v55, v55, v51
	v_mul_f32_e32 v56, v52, v56
	v_mul_f32_e32 v57, v53, v57
	v_mul_f32_e32 v58, v54, v58
	v_mul_f32_e32 v59, v55, v59
	v_cvt_pk_bf16_f32 v60, v56, v57
	v_cvt_pk_bf16_f32 v61, v58, v59
	global_store_dwordx2 v234, v[60:61], s[24:25]
	v_lshlrev_b32_e32 v48, 16, v228
	v_and_b32_e32 v49, 0xffff0000, v228
	v_lshlrev_b32_e32 v50, 16, v229
	v_and_b32_e32 v51, 0xffff0000, v229
	v_mul_f32_e32 v52, 0xbfb8aa3b, v48
	v_mul_f32_e32 v53, 0xbfb8aa3b, v49
	v_mul_f32_e32 v54, 0xbfb8aa3b, v50
	v_mul_f32_e32 v55, 0xbfb8aa3b, v51
	v_exp_f32_e32 v52, v52
	v_exp_f32_e32 v53, v53
	v_exp_f32_e32 v54, v54
	v_exp_f32_e32 v55, v55
	v_mul_f32_e32 v56, v4, v46
	v_mul_f32_e32 v57, v5, v46
	v_mul_f32_e32 v58, v6, v46
	v_mul_f32_e32 v59, v7, v46
	v_add_f32_e32 v52, 1.0, v52
	v_add_f32_e32 v53, 1.0, v53
	v_add_f32_e32 v54, 1.0, v54
	v_add_f32_e32 v55, 1.0, v55
	v_rcp_f32_e32 v52, v52
	v_rcp_f32_e32 v53, v53
	v_rcp_f32_e32 v54, v54
	v_rcp_f32_e32 v55, v55
	v_mul_f32_e32 v56, v208, v56
	v_mul_f32_e32 v57, v209, v57
	v_mul_f32_e32 v58, v210, v58
	v_mul_f32_e32 v59, v211, v59
	v_mul_f32_e32 v52, v52, v48
	v_mul_f32_e32 v53, v53, v49
	v_mul_f32_e32 v54, v54, v50
	v_mul_f32_e32 v55, v55, v51
	v_mul_f32_e32 v56, v52, v56
	v_mul_f32_e32 v57, v53, v57
	v_mul_f32_e32 v58, v54, v58
	v_mul_f32_e32 v59, v55, v59
	v_cvt_pk_bf16_f32 v60, v56, v57
	v_cvt_pk_bf16_f32 v61, v58, v59
	s_add_u32 s24, s24, s99
	s_addc_u32 s25, s25, 0
	global_store_dwordx2 v232, v[60:61], s[24:25]
	v_lshlrev_b32_e32 v48, 16, v230
	v_and_b32_e32 v49, 0xffff0000, v230
	v_lshlrev_b32_e32 v50, 16, v231
	v_and_b32_e32 v51, 0xffff0000, v231
	v_mul_f32_e32 v52, 0xbfb8aa3b, v48
	v_mul_f32_e32 v53, 0xbfb8aa3b, v49
	v_mul_f32_e32 v54, 0xbfb8aa3b, v50
	v_mul_f32_e32 v55, 0xbfb8aa3b, v51
	v_exp_f32_e32 v52, v52
	v_exp_f32_e32 v53, v53
	v_exp_f32_e32 v54, v54
	v_exp_f32_e32 v55, v55
	v_mul_f32_e32 v56, v0, v46
	v_mul_f32_e32 v57, v1, v46
	v_mul_f32_e32 v58, v2, v46
	v_mul_f32_e32 v59, v3, v46
	v_add_f32_e32 v52, 1.0, v52
	v_add_f32_e32 v53, 1.0, v53
	v_add_f32_e32 v54, 1.0, v54
	v_add_f32_e32 v55, 1.0, v55
	v_rcp_f32_e32 v52, v52
	v_rcp_f32_e32 v53, v53
	v_rcp_f32_e32 v54, v54
	v_rcp_f32_e32 v55, v55
	v_mul_f32_e32 v56, v212, v56
	v_mul_f32_e32 v57, v213, v57
	v_mul_f32_e32 v58, v214, v58
	v_mul_f32_e32 v59, v215, v59
	v_mul_f32_e32 v52, v52, v48
	v_mul_f32_e32 v53, v53, v49
	v_mul_f32_e32 v54, v54, v50
	v_mul_f32_e32 v55, v55, v51
	v_mul_f32_e32 v56, v52, v56
	v_mul_f32_e32 v57, v53, v57
	v_mul_f32_e32 v58, v54, v58
	v_mul_f32_e32 v59, v55, v59
	v_cvt_pk_bf16_f32 v60, v56, v57
	v_cvt_pk_bf16_f32 v61, v58, v59
	global_store_dwordx2 v234, v[60:61], s[24:25]
	s_branch .LBB0_1087

.LBB0_1151:
	s_add_u32 s8, s20, 0x10a40000
	s_addc_u32 s9, s21, 0
	s_add_u32 s6, s20, 0x11048000
	s_addc_u32 s7, s21, 0
	s_abs_i32 s0, s29
	v_cvt_f32_u32_e32 v0, s0
	s_sub_i32 s1, s29, s28
	s_add_i32 s4, s1, 0x7f
	s_sub_i32 s1, 0xffffff81, s1
	v_rcp_iflag_f32_e32 v0, v0
	s_xor_b32 s5, s4, s29
	s_max_i32 s1, s4, s1
	s_sub_i32 s4, 0, s0
	v_mul_f32_e32 v0, 0x4f7ffffe, v0
	v_cvt_u32_f32_e32 v0, v0
	s_ashr_i32 s5, s5, 31
	s_waitcnt vmcnt(16)
	v_bfe_u32 v140, v138, 6, 1
	v_bfe_u32 v139, v138, 4, 2
	v_readfirstlane_b32 s10, v0
	s_mul_i32 s4, s4, s10
	s_mul_hi_u32 s4, s10, s4
	s_add_i32 s10, s10, s4
	s_mul_hi_u32 s4, s1, s10
	s_mul_i32 s10, s4, s0
	s_sub_i32 s1, s1, s10
	s_add_i32 s10, s4, 1
	s_sub_i32 s11, s1, s0
	s_cmp_ge_u32 s1, s0
	s_cselect_b32 s4, s10, s4
	s_cselect_b32 s1, s11, s1
	s_add_i32 s10, s4, 1
	s_cmp_ge_u32 s1, s0
	s_cselect_b32 s0, s10, s4
	s_xor_b32 s0, s0, s5
	s_sub_i32 s0, s0, s5
	s_lshl_b32 s56, s0, 3
	s_cmp_ge_i32 s88, s56
	s_mov_b32 s11, 0
	s_cbranch_scc1 .LBB0_1164
	v_lshlrev_b32_e32 v1, 3, v139
	v_and_b32_e32 v0, 15, v138
	v_lshl_or_b32 v1, v140, 7, v1
	s_movk_i32 s4, 0x110
	v_add_u32_e32 v3, 0x100, v138
	v_add_u32_e32 v4, 0x200, v138
	v_add_u32_e32 v5, 0x300, v138
	v_add_u32_e32 v6, 0x400, v138
	v_add_u32_e32 v7, 0x500, v138
	v_add_u32_e32 v8, 0x600, v138
	v_add_u32_e32 v9, 0x700, v138
	v_lshlrev_b32_e32 v2, 4, v138
	v_ashrrev_i32_e32 v141, 4, v138
	v_mad_u32_u24 v142, v0, s4, v1
	v_or_b32_e32 v0, 0x70, v138
	v_ashrrev_i32_e32 v143, 4, v3
	v_ashrrev_i32_e32 v144, 4, v4
	v_ashrrev_i32_e32 v145, 4, v5
	v_ashrrev_i32_e32 v146, 4, v6
	v_ashrrev_i32_e32 v147, 4, v7
	v_ashrrev_i32_e32 v148, 4, v8
	v_ashrrev_i32_e32 v149, 4, v9
	v_and_b32_e32 v128, 0xf0, v2
	v_mov_b32_e32 v129, 0
	v_mul_lo_u32 v2, v141, s4
	s_movk_i32 s5, 0x80
	v_mul_lo_u32 v0, v0, s4
	v_mul_lo_u32 v3, v143, s4
	v_mul_lo_u32 v4, v144, s4
	v_mul_lo_u32 v5, v145, s4
	v_mul_lo_u32 v6, v146, s4
	v_mul_lo_u32 v7, v147, s4
	v_mul_lo_u32 v8, v148, s4
	v_mul_lo_u32 v9, v149, s4
	v_and_b32_e32 v10, 0xffffff80, v138
	v_lshl_add_u64 v[130:131], s[6:7], 0, v[128:129]
	v_cmp_gt_u32_e64 s[0:1], s5, v138
	v_cmp_eq_u32_e64 s[4:5], s5, v10
	s_lshl_b32 s57, s88, 7
	s_lshl_b32 s58, s89, 7
	s_mov_b64 s[46:47], 0
	s_mov_b64 s[12:13], 0x4000
	s_mov_b64 s[14:15], 0x8000
	s_mov_b64 s[16:17], 0xc000
	s_mov_b64 s[30:31], 0x20000
	s_mov_b64 s[34:35], 0x14000
	s_mov_b64 s[36:37], 0x18000
	s_mov_b64 s[38:39], 0x1c000
	s_mov_b64 s[100:101], 0x10000
	v_and_b32_e32 v226, 0x7f, v138
	v_lshlrev_b32_e32 v226, 4, v226
	v_mov_b32_e32 v227, 0
	v_lshrrev_b32_e32 v228, 7, v138
	s_mov_b64 s[40:41], 0x10a40040
	s_mov_b64 s[42:43], 0x10a60040
	v_add_u32_e32 v150, v1, v0
	v_add_u32_e32 v151, v128, v2
	v_add_u32_e32 v152, v128, v3
	v_add_u32_e32 v153, v128, v4
	v_add_u32_e32 v154, v128, v5
	v_add_u32_e32 v155, v128, v6
	v_add_u32_e32 v156, v128, v7
	v_add_u32_e32 v157, v128, v8
	v_add_u32_e32 v158, v128, v9
	s_branch .LBB0_1154

.LBB0_1154:
	s_lshr_b32 s10, s88, 3
	s_mul_i32 s10, s10, s29
	s_add_i32 s10, s10, s28
	v_mov_b32_e32 v2, v181
	s_lshl_b32 s59, s10, 8
	s_lshl_b32 s10, s88, 7
	v_ashrrev_i32_e32 v163, 2, v2
	v_add_u32_e32 v0, s59, v228
	v_lshlrev_b32_e32 v3, 3, v2
	v_ashrrev_i32_e32 v1, 31, v0
	v_bitop3_b32 v4, v3, 24, v2 bitop3:0x48
	v_lshlrev_b32_e32 v165, 4, v2
	s_and_b32 s10, s10, 0x380
	v_lshlrev_b64 v[0:1], 13, v[0:1]
	s_and_b64 vcc, exec, s[46:47]
	v_add_u32_e32 v164, 0x1000, v165
	v_add_u32_e32 v162, 0x2000, v165
	v_add_u32_e32 v161, 0x3000, v165
	v_add_u32_e32 v160, 0x4000, v165
	v_add_u32_e32 v159, 0x5000, v165
	v_lshlrev_b32_e32 v132, 1, v4
	s_cbranch_vccnz .LBB0_1156
	v_lshl_add_u64 v[4:5], s[20:21], 0, v[0:1]
	v_mov_b32_e32 v133, v129
	v_readfirstlane_b32 s24, v165
	v_lshl_add_u64 v[4:5], v[4:5], 0, v[226:227]
	v_add_u32_e32 v6, s10, v163
	s_mov_b32 m0, s24
	v_readfirstlane_b32 s24, v164
	v_ashrrev_i32_e32 v7, 31, v6
	s_barrier
	global_load_lds_dwordx4 v[4:5], off
	v_lshl_add_u64 v[8:9], v[4:5], 0, s[12:13]
	s_mov_b32 m0, s24
	v_readfirstlane_b32 s24, v162
	v_lshlrev_b64 v[6:7], 11, v[6:7]
	global_load_lds_dwordx4 v[8:9], off
	v_lshl_add_u64 v[8:9], v[4:5], 0, s[14:15]
	s_mov_b32 m0, s24
	v_readfirstlane_b32 s24, v161
	v_lshl_add_u64 v[6:7], s[8:9], 0, v[6:7]
	global_load_lds_dwordx4 v[8:9], off
	v_lshl_add_u64 v[4:5], v[4:5], 0, s[16:17]
	s_mov_b32 m0, s24
	v_readfirstlane_b32 s24, v160
	v_lshl_add_u64 v[6:7], v[6:7], 0, v[132:133]
	global_load_lds_dwordx4 v[4:5], off
	s_mov_b32 m0, s24
	v_readfirstlane_b32 s24, v159
	global_load_lds_dwordx4 v[6:7], off
	v_lshl_add_u64 v[4:5], v[6:7], 0, s[30:31]
	s_mov_b32 m0, s24
	s_nop 0
	global_load_lds_dwordx4 v[4:5], off
.LBB0_1156:
	v_xor_b32_e32 v3, v3, v2
	v_lshlrev_b32_e32 v2, 6, v2
	v_and_b32_e32 v168, 0x1000, v2
	v_and_b32_e32 v166, 0x3c0, v2
	v_and_b32_e32 v167, 0xffffe000, v2
	v_lshlrev_b32_e32 v2, 1, v3
	v_and_b32_e32 v128, 48, v2
	s_and_b32 s24, s57, 0x380
	v_lshl_add_u64 v[0:1], v[0:1], 0, v[226:227]
	v_lshl_add_u64 v[134:135], s[20:21], 0, v[0:1]
	v_add_u32_e32 v0, s24, v163
	v_ashrrev_i32_e32 v1, 31, v0
	v_lshlrev_b64 v[0:1], 11, v[0:1]
	v_or_b32_e32 v0, v0, v128
	v_lshl_add_u64 v[136:137], s[20:21], 0, v[0:1]
	v_mov_b32_e32 v0, 0
	v_and_b32_e32 v133, 48, v3
	s_mov_b32 s46, 1
	s_mov_b64 s[44:45], 0
	v_mov_b32_e32 v1, v0
	v_mov_b32_e32 v2, v0
	v_mov_b32_e32 v3, v0
	v_mov_b32_e32 v4, v0
	v_mov_b32_e32 v5, v0
	v_mov_b32_e32 v6, v0
	v_mov_b32_e32 v7, v0
	v_mov_b32_e32 v8, v0
	v_mov_b32_e32 v9, v0
	v_mov_b32_e32 v10, v0
	v_mov_b32_e32 v11, v0
	v_mov_b32_e32 v12, v0
	v_mov_b32_e32 v13, v0
	v_mov_b32_e32 v14, v0
	v_mov_b32_e32 v15, v0
	v_mov_b32_e32 v16, v0
	v_mov_b32_e32 v17, v0
	v_mov_b32_e32 v18, v0
	v_mov_b32_e32 v19, v0
	v_mov_b32_e32 v20, v0
	v_mov_b32_e32 v21, v0
	v_mov_b32_e32 v22, v0
	v_mov_b32_e32 v23, v0
	v_mov_b32_e32 v24, v0
	v_mov_b32_e32 v25, v0
	v_mov_b32_e32 v26, v0
	v_mov_b32_e32 v27, v0
	v_mov_b32_e32 v28, v0
	v_mov_b32_e32 v29, v0
	v_mov_b32_e32 v30, v0
	v_mov_b32_e32 v31, v0
	v_mov_b32_e32 v32, v0
	v_mov_b32_e32 v33, v0
	v_mov_b32_e32 v34, v0
	v_mov_b32_e32 v35, v0
	v_mov_b32_e32 v36, v0
	v_mov_b32_e32 v37, v0
	v_mov_b32_e32 v38, v0
	v_mov_b32_e32 v39, v0
	v_mov_b32_e32 v40, v0
	v_mov_b32_e32 v41, v0
	v_mov_b32_e32 v42, v0
	v_mov_b32_e32 v43, v0
	v_mov_b32_e32 v44, v0
	v_mov_b32_e32 v45, v0
	v_mov_b32_e32 v46, v0
	v_mov_b32_e32 v47, v0
	v_mov_b32_e32 v48, v0
	v_mov_b32_e32 v49, v0
	v_mov_b32_e32 v50, v0
	v_mov_b32_e32 v51, v0
	v_mov_b32_e32 v52, v0
	v_mov_b32_e32 v53, v0
	v_mov_b32_e32 v54, v0
	v_mov_b32_e32 v55, v0
	v_mov_b32_e32 v56, v0
	v_mov_b32_e32 v57, v0
	v_mov_b32_e32 v58, v0
	v_mov_b32_e32 v59, v0
	v_mov_b32_e32 v60, v0
	v_mov_b32_e32 v61, v0
	v_mov_b32_e32 v62, v0
	v_mov_b32_e32 v63, v0
	v_mov_b32_e32 v64, v0
	v_mov_b32_e32 v65, v0
	v_mov_b32_e32 v66, v0
	v_mov_b32_e32 v67, v0
	v_mov_b32_e32 v68, v0
	v_mov_b32_e32 v69, v0
	v_mov_b32_e32 v70, v0
	v_mov_b32_e32 v71, v0
	v_mov_b32_e32 v72, v0
	v_mov_b32_e32 v73, v0
	v_mov_b32_e32 v74, v0
	v_mov_b32_e32 v75, v0
	v_mov_b32_e32 v76, v0
	v_mov_b32_e32 v77, v0
	v_mov_b32_e32 v78, v0
	v_mov_b32_e32 v79, v0
	v_mov_b32_e32 v80, v0
	v_mov_b32_e32 v81, v0
	v_mov_b32_e32 v82, v0
	v_mov_b32_e32 v83, v0
	v_mov_b32_e32 v84, v0
	v_mov_b32_e32 v85, v0
	v_mov_b32_e32 v86, v0
	v_mov_b32_e32 v87, v0
	v_mov_b32_e32 v88, v0
	v_mov_b32_e32 v89, v0
	v_mov_b32_e32 v90, v0
	v_mov_b32_e32 v91, v0
	v_mov_b32_e32 v92, v0
	v_mov_b32_e32 v93, v0
	v_mov_b32_e32 v94, v0
	v_mov_b32_e32 v95, v0
	v_mov_b32_e32 v96, v0
	v_mov_b32_e32 v97, v0
	v_mov_b32_e32 v98, v0
	v_mov_b32_e32 v99, v0
	v_mov_b32_e32 v100, v0
	v_mov_b32_e32 v101, v0
	v_mov_b32_e32 v102, v0
	v_mov_b32_e32 v103, v0
	v_mov_b32_e32 v104, v0
	v_mov_b32_e32 v105, v0
	v_mov_b32_e32 v106, v0
	v_mov_b32_e32 v107, v0
	v_mov_b32_e32 v108, v0
	v_mov_b32_e32 v109, v0
	v_mov_b32_e32 v110, v0
	v_mov_b32_e32 v111, v0
	v_mov_b32_e32 v112, v0
	v_mov_b32_e32 v113, v0
	v_mov_b32_e32 v114, v0
	v_mov_b32_e32 v115, v0
	v_mov_b32_e32 v116, v0
	v_mov_b32_e32 v117, v0
	v_mov_b32_e32 v118, v0
	v_mov_b32_e32 v119, v0
	v_mov_b32_e32 v120, v0
	v_mov_b32_e32 v121, v0
	v_mov_b32_e32 v122, v0
	v_mov_b32_e32 v123, v0
	v_mov_b32_e32 v124, v0
	v_mov_b32_e32 v125, v0
	v_mov_b32_e32 v126, v0
	v_mov_b32_e32 v127, v0
	s_waitcnt vmcnt(0) lgkmcnt(0)
	s_barrier
.LBB0_1157:
	s_lshl_b64 s[98:99], s[44:45], 10
	s_bitcmp1_b32 s46, 0
	s_cselect_b32 s24, 0x6000, 0
	v_add_u32_e32 v128, s24, v165
	v_lshl_add_u64 v[170:171], v[134:135], 0, s[98:99]
	v_readfirstlane_b32 s24, v128
	v_add_u32_e32 v169, 0x1000, v128
	v_lshl_add_u64 v[172:173], v[170:171], 0, s[100:101]
	s_mov_b32 m0, s24
	v_readfirstlane_b32 s24, v169
	v_add_u32_e32 v169, 0x2000, v128
	global_load_lds_dwordx4 v[172:173], off
	v_lshl_add_u64 v[172:173], v[170:171], 0, s[34:35]
	s_mov_b32 m0, s24
	v_readfirstlane_b32 s24, v169
	v_add_u32_e32 v169, 0x3000, v128
	global_load_lds_dwordx4 v[172:173], off
	v_lshl_add_u64 v[172:173], v[170:171], 0, s[36:37]
	s_mov_b32 m0, s24
	v_readfirstlane_b32 s24, v169
	global_load_lds_dwordx4 v[172:173], off
	v_lshl_add_u64 v[170:171], v[170:171], 0, s[38:39]
	s_mov_b32 m0, s24
	v_add_u32_e32 v169, 0x4000, v128
	global_load_lds_dwordx4 v[170:171], off
	v_lshl_add_u64 v[170:171], v[136:137], 0, s[44:45]
	v_readfirstlane_b32 s24, v169
	v_add_u32_e32 v128, 0x5000, v128
	v_lshl_add_u64 v[172:173], v[170:171], 0, s[40:41]
	s_mov_b32 m0, s24
	v_readfirstlane_b32 s24, v128
	global_load_lds_dwordx4 v[172:173], off
	v_lshl_add_u64 v[170:171], v[170:171], 0, s[42:43]
	s_mov_b32 m0, s24
	s_nop 0
	global_load_lds_dwordx4 v[170:171], off
	s_cselect_b32 s24, 0, 0x6000
	v_or_b32_e32 v128, s24, v168
	v_add3_u32 v128, v128, v166, v133
	ds_read_b128 v[170:173], v128 offset:16384
	ds_read_b128 v[174:177], v128 offset:17408
	ds_read_b128 v[184:187], v128 offset:18432
	ds_read_b128 v[188:191], v128 offset:19456
	v_add_u32_e32 v128, s24, v167
	v_add3_u32 v128, v128, v166, v133
	ds_read_b128 v[192:195], v128
	ds_read_b128 v[196:199], v128 offset:1024
	ds_read_b128 v[200:203], v128 offset:2048
	ds_read_b128 v[204:207], v128 offset:3072
	ds_read_b128 v[208:211], v128 offset:4096
	ds_read_b128 v[212:215], v128 offset:5120
	ds_read_b128 v[216:219], v128 offset:6144
	ds_read_b128 v[220:223], v128 offset:7168
	s_setprio 1
	s_waitcnt lgkmcnt(0)
	v_mfma_f32_16x16x32_bf16 v[124:127], v[170:173], v[192:195], v[124:127]
	v_mfma_f32_16x16x32_bf16 v[120:123], v[174:177], v[192:195], v[120:123]
	v_mfma_f32_16x16x32_bf16 v[116:119], v[184:187], v[192:195], v[116:119]
	v_mfma_f32_16x16x32_bf16 v[112:115], v[188:191], v[192:195], v[112:115]
	v_mfma_f32_16x16x32_bf16 v[108:111], v[170:173], v[196:199], v[108:111]
	v_mfma_f32_16x16x32_bf16 v[104:107], v[174:177], v[196:199], v[104:107]
	v_mfma_f32_16x16x32_bf16 v[100:103], v[184:187], v[196:199], v[100:103]
	v_mfma_f32_16x16x32_bf16 v[96:99], v[188:191], v[196:199], v[96:99]
	v_mfma_f32_16x16x32_bf16 v[92:95], v[170:173], v[200:203], v[92:95]
	v_mfma_f32_16x16x32_bf16 v[88:91], v[174:177], v[200:203], v[88:91]
	v_mfma_f32_16x16x32_bf16 v[84:87], v[184:187], v[200:203], v[84:87]
	v_mfma_f32_16x16x32_bf16 v[80:83], v[188:191], v[200:203], v[80:83]
	v_mfma_f32_16x16x32_bf16 v[76:79], v[170:173], v[204:207], v[76:79]
	v_mfma_f32_16x16x32_bf16 v[72:75], v[174:177], v[204:207], v[72:75]
	v_mfma_f32_16x16x32_bf16 v[68:71], v[184:187], v[204:207], v[68:71]
	v_mfma_f32_16x16x32_bf16 v[64:67], v[188:191], v[204:207], v[64:67]
	v_mfma_f32_16x16x32_bf16 v[60:63], v[170:173], v[208:211], v[60:63]
	v_mfma_f32_16x16x32_bf16 v[56:59], v[174:177], v[208:211], v[56:59]
	v_mfma_f32_16x16x32_bf16 v[52:55], v[184:187], v[208:211], v[52:55]
	v_mfma_f32_16x16x32_bf16 v[48:51], v[188:191], v[208:211], v[48:51]
	v_mfma_f32_16x16x32_bf16 v[44:47], v[170:173], v[212:215], v[44:47]
	v_mfma_f32_16x16x32_bf16 v[40:43], v[174:177], v[212:215], v[40:43]
	v_mfma_f32_16x16x32_bf16 v[36:39], v[184:187], v[212:215], v[36:39]
	v_mfma_f32_16x16x32_bf16 v[32:35], v[188:191], v[212:215], v[32:35]
	v_mfma_f32_16x16x32_bf16 v[28:31], v[170:173], v[216:219], v[28:31]
	v_mfma_f32_16x16x32_bf16 v[24:27], v[174:177], v[216:219], v[24:27]
	v_mfma_f32_16x16x32_bf16 v[20:23], v[184:187], v[216:219], v[20:23]
	v_mfma_f32_16x16x32_bf16 v[16:19], v[188:191], v[216:219], v[16:19]
	v_mfma_f32_16x16x32_bf16 v[12:15], v[170:173], v[220:223], v[12:15]
	v_mfma_f32_16x16x32_bf16 v[8:11], v[174:177], v[220:223], v[8:11]
	v_mfma_f32_16x16x32_bf16 v[4:7], v[184:187], v[220:223], v[4:7]
	v_mfma_f32_16x16x32_bf16 v[0:3], v[188:191], v[220:223], v[0:3]
	s_setprio 0
	s_add_u32 s44, s44, 64
	s_addc_u32 s45, s45, 0
	s_add_i32 s46, s46, 1
	s_cmpk_eq_i32 s44, 0x7c0
	s_waitcnt vmcnt(0)
	s_barrier
	s_cbranch_scc0 .LBB0_1157
	s_add_i32 s88, s88, s89
	s_cmp_ge_i32 s88, s56
	s_cselect_b64 s[44:45], -1, 0
	s_cmp_lt_i32 s88, s56
	v_add3_u32 v128, v168, v166, v133
	ds_read_b128 v[134:137], v128 offset:40960
	ds_read_b128 v[168:171], v128 offset:41984
	ds_read_b128 v[172:175], v128 offset:43008
	ds_read_b128 v[176:179], v128 offset:44032
	v_add3_u32 v128, v167, v166, v133
	ds_read_b128 v[184:187], v128 offset:24576
	ds_read_b128 v[188:191], v128 offset:25600
	ds_read_b128 v[192:195], v128 offset:26624
	ds_read_b128 v[196:199], v128 offset:27648
	ds_read_b128 v[200:203], v128 offset:28672
	ds_read_b128 v[204:207], v128 offset:29696
	ds_read_b128 v[208:211], v128 offset:30720
	ds_read_b128 v[212:215], v128 offset:31744
	s_setprio 1
	s_waitcnt lgkmcnt(7)
	v_mfma_f32_16x16x32_bf16 v[124:127], v[134:137], v[184:187], v[124:127]
	v_mfma_f32_16x16x32_bf16 v[120:123], v[168:171], v[184:187], v[120:123]
	v_mfma_f32_16x16x32_bf16 v[116:119], v[172:175], v[184:187], v[116:119]
	v_mfma_f32_16x16x32_bf16 v[112:115], v[176:179], v[184:187], v[112:115]
	s_waitcnt lgkmcnt(6)
	v_mfma_f32_16x16x32_bf16 v[108:111], v[134:137], v[188:191], v[108:111]
	v_mfma_f32_16x16x32_bf16 v[104:107], v[168:171], v[188:191], v[104:107]
	v_mfma_f32_16x16x32_bf16 v[100:103], v[172:175], v[188:191], v[100:103]
	v_mfma_f32_16x16x32_bf16 v[96:99], v[176:179], v[188:191], v[96:99]
	s_waitcnt lgkmcnt(5)
	v_mfma_f32_16x16x32_bf16 v[92:95], v[134:137], v[192:195], v[92:95]
	v_mfma_f32_16x16x32_bf16 v[88:91], v[168:171], v[192:195], v[88:91]
	v_mfma_f32_16x16x32_bf16 v[84:87], v[172:175], v[192:195], v[84:87]
	v_mfma_f32_16x16x32_bf16 v[80:83], v[176:179], v[192:195], v[80:83]
	s_waitcnt lgkmcnt(4)
	v_mfma_f32_16x16x32_bf16 v[76:79], v[134:137], v[196:199], v[76:79]
	v_mfma_f32_16x16x32_bf16 v[72:75], v[168:171], v[196:199], v[72:75]
	v_mfma_f32_16x16x32_bf16 v[68:71], v[172:175], v[196:199], v[68:71]
	v_mfma_f32_16x16x32_bf16 v[64:67], v[176:179], v[196:199], v[64:67]
	s_waitcnt lgkmcnt(3)
	v_mfma_f32_16x16x32_bf16 v[60:63], v[134:137], v[200:203], v[60:63]
	v_mfma_f32_16x16x32_bf16 v[56:59], v[168:171], v[200:203], v[56:59]
	v_mfma_f32_16x16x32_bf16 v[52:55], v[172:175], v[200:203], v[52:55]
	v_mfma_f32_16x16x32_bf16 v[48:51], v[176:179], v[200:203], v[48:51]
	s_waitcnt lgkmcnt(2)
	v_mfma_f32_16x16x32_bf16 v[44:47], v[134:137], v[204:207], v[44:47]
	v_mfma_f32_16x16x32_bf16 v[40:43], v[168:171], v[204:207], v[40:43]
	v_mfma_f32_16x16x32_bf16 v[36:39], v[172:175], v[204:207], v[36:39]
	v_mfma_f32_16x16x32_bf16 v[32:35], v[176:179], v[204:207], v[32:35]
	s_waitcnt lgkmcnt(1)
	v_mfma_f32_16x16x32_bf16 v[28:31], v[134:137], v[208:211], v[28:31]
	v_mfma_f32_16x16x32_bf16 v[24:27], v[168:171], v[208:211], v[24:27]
	v_mfma_f32_16x16x32_bf16 v[20:23], v[172:175], v[208:211], v[20:23]
	v_mfma_f32_16x16x32_bf16 v[16:19], v[176:179], v[208:211], v[16:19]
	s_waitcnt lgkmcnt(0)
	v_mfma_f32_16x16x32_bf16 v[12:15], v[134:137], v[212:215], v[12:15]
	v_mfma_f32_16x16x32_bf16 v[8:11], v[168:171], v[212:215], v[8:11]
	v_mfma_f32_16x16x32_bf16 v[4:7], v[172:175], v[212:215], v[4:7]
	v_mfma_f32_16x16x32_bf16 v[0:3], v[176:179], v[212:215], v[0:3]
	s_setprio 0
	s_barrier
	s_cbranch_scc0 .LBB0_1160
	s_lshr_b32 s24, s88, 3
	s_mul_i32 s24, s24, s29
	s_add_i32 s24, s24, s28
	s_lshl_b32 s25, s88, 7
	s_and_b32 s25, s25, 0x380
	v_lshl_add_u32 v134, s24, 8, v228
	v_ashrrev_i32_e32 v135, 31, v134
	v_add_u32_e32 v136, s25, v163
	v_lshlrev_b64 v[134:135], 13, v[134:135]
	v_ashrrev_i32_e32 v137, 31, v136
	v_lshl_add_u64 v[134:135], s[20:21], 0, v[134:135]
	v_mov_b32_e32 v133, v129
	v_lshlrev_b64 v[136:137], 11, v[136:137]
	v_readfirstlane_b32 s24, v165
	v_lshl_add_u64 v[134:135], v[134:135], 0, v[226:227]
	v_lshl_add_u64 v[136:137], s[8:9], 0, v[136:137]
	s_mov_b32 m0, s24
	v_readfirstlane_b32 s24, v164
	v_lshl_add_u64 v[132:133], v[136:137], 0, v[132:133]
	global_load_lds_dwordx4 v[134:135], off
	v_lshl_add_u64 v[136:137], v[134:135], 0, s[12:13]
	s_mov_b32 m0, s24
	v_readfirstlane_b32 s24, v162
	global_load_lds_dwordx4 v[136:137], off
	v_lshl_add_u64 v[136:137], v[134:135], 0, s[14:15]
	s_mov_b32 m0, s24
	v_readfirstlane_b32 s24, v161
	global_load_lds_dwordx4 v[136:137], off
	v_lshl_add_u64 v[134:135], v[134:135], 0, s[16:17]
	s_mov_b32 m0, s24
	v_readfirstlane_b32 s24, v160
	global_load_lds_dwordx4 v[134:135], off
	s_mov_b32 m0, s24
	v_readfirstlane_b32 s24, v159
	global_load_lds_dwordx4 v[132:133], off
	v_lshl_add_u64 v[132:133], v[132:133], 0, s[30:31]
	s_mov_b32 m0, s24
	s_nop 0
	global_load_lds_dwordx4 v[132:133], off
